# ctx split-K reduction phase (row loop): all 40 loads of a row (8 partials x 4 column groups, residual, gate) issued together then summed in the original order (were 40 load-wait pairs)
# speedup vs baseline: 1.0106x; 1.0028x over previous
; __device__ __forceinline__ void phase_xs_ctx(Ctx& F, float* xctx, const float* part, const float* gate4, const float* g, const float* modl, float* ss1, bf16* XS) {
;     ...
;     for (int r = gw; r < MC; r += NGW) {
;         const int row = ML + r;
;         float* xr = xctx + (size_t)r * DM; const float* sc = modl + 4 * MODW + DM;
;         f32x4 v[4]; float ss = 0.f;
; #pragma unroll
;         for (int j = 0; j < 4; ++j) { const int c = 256 * j + 4 * lane; f32x4 a = {0.f, 0.f, 0.f, 0.f};
; #pragma unroll
;             for (int ks = 0; ks < KSPLIT; ++ks) a += *(const f32x4*)(part + ((size_t)ks * MC + r) * DM + c);
;             v[j] = *(const f32x4*)(xr + c) + *(const f32x4*)(gate4 + c) * a; *(f32x4*)(xr + c) = v[j];
;             ss += (v[j][0] * v[j][0] + v[j][1] * v[j][1]) + (v[j][2] * v[j][2] + v[j][3] * v[j][3]); }
.LBB0_25:
	s_add_i32 s8, s12, 0x8000
	s_ashr_i32 s9, s8, 31
	v_add_co_u32_e32 v12, vcc, 0xfe400000, v42
	s_nop 1
	v_addc_co_u32_e32 v13, vcc, -1, v43, vcc
	v_add_co_u32_e32 v14, vcc, 0xfe800000, v42
	s_nop 1
	v_addc_co_u32_e32 v15, vcc, -1, v43, vcc
	v_add_co_u32_e32 v46, vcc, 0xfec00000, v42
	s_nop 1
	v_addc_co_u32_e32 v47, vcc, -1, v43, vcc
	v_add_co_u32_e32 v48, vcc, 0xff000000, v42
	s_nop 1
	v_addc_co_u32_e32 v49, vcc, -1, v43, vcc
	v_add_co_u32_e32 v50, vcc, 0xff400000, v42
	s_nop 1
	v_addc_co_u32_e32 v51, vcc, -1, v43, vcc
	v_add_co_u32_e32 v52, vcc, 0xff800000, v42
	s_nop 1
	v_addc_co_u32_e32 v53, vcc, -1, v43, vcc
	v_add_co_u32_e32 v54, vcc, 0xffc00000, v42
	s_nop 1
	v_addc_co_u32_e32 v55, vcc, -1, v43, vcc
	v_add_co_u32_e32 v44, vcc, 0xf9e00000, v42
	s_nop 1
	v_addc_co_u32_e32 v45, vcc, -1, v43, vcc
	global_load_dwordx4 v[72:75], v[12:13], off offset:-3072
	global_load_dwordx4 v[76:79], v[14:15], off offset:-3072
	global_load_dwordx4 v[80:83], v[46:47], off offset:-3072
	global_load_dwordx4 v[84:87], v[48:49], off offset:-3072
	global_load_dwordx4 v[88:91], v[50:51], off offset:-3072
	global_load_dwordx4 v[92:95], v[52:53], off offset:-3072
	global_load_dwordx4 v[96:99], v[54:55], off offset:-3072
	global_load_dwordx4 v[100:103], v[42:43], off offset:-3072
	global_load_dwordx4 v[104:107], v[12:13], off offset:-2048
	global_load_dwordx4 v[108:111], v[14:15], off offset:-2048
	global_load_dwordx4 v[112:115], v[46:47], off offset:-2048
	global_load_dwordx4 v[116:119], v[48:49], off offset:-2048
	global_load_dwordx4 v[120:123], v[50:51], off offset:-2048
	global_load_dwordx4 v[124:127], v[52:53], off offset:-2048
	global_load_dwordx4 v[128:131], v[54:55], off offset:-2048
	global_load_dwordx4 v[132:135], v[42:43], off offset:-2048
	global_load_dwordx4 v[136:139], v[12:13], off offset:-1024
	global_load_dwordx4 v[140:143], v[14:15], off offset:-1024
	global_load_dwordx4 v[144:147], v[46:47], off offset:-1024
	global_load_dwordx4 v[148:151], v[48:49], off offset:-1024
	global_load_dwordx4 v[152:155], v[50:51], off offset:-1024
	global_load_dwordx4 v[156:159], v[52:53], off offset:-1024
	global_load_dwordx4 v[160:163], v[54:55], off offset:-1024
	global_load_dwordx4 v[164:167], v[42:43], off offset:-1024
	global_load_dwordx4 v[168:171], v[12:13], off
	global_load_dwordx4 v[172:175], v[14:15], off
	global_load_dwordx4 v[176:179], v[46:47], off
	global_load_dwordx4 v[180:183], v[48:49], off
	global_load_dwordx4 v[184:187], v[50:51], off
	global_load_dwordx4 v[188:191], v[52:53], off
	global_load_dwordx4 v[192:195], v[54:55], off
	global_load_dwordx4 v[196:199], v[42:43], off
	global_load_dwordx4 v[0:3], v[44:45], off offset:-3072
	global_load_dwordx4 v[4:7], v[44:45], off offset:-2048
	global_load_dwordx4 v[8:11], v[44:45], off offset:-1024
	global_load_dwordx4 v[12:15], v[44:45], off
	global_load_dwordx4 v[66:69], v[18:19], off
	global_load_dwordx4 v[200:203], v[20:21], off
	global_load_dwordx4 v[62:65], v[22:23], off
	global_load_dwordx4 v[48:51], v[24:25], off
	s_waitcnt vmcnt(3)
	v_pk_add_f32 v[52:53], v[74:75], 0 op_sel_hi:[1,0]
	v_pk_add_f32 v[54:55], v[72:73], 0 op_sel_hi:[1,0]
	v_pk_add_f32 v[52:53], v[52:53], v[78:79]
	v_pk_add_f32 v[54:55], v[54:55], v[76:77]
	v_pk_add_f32 v[52:53], v[52:53], v[82:83]
	v_pk_add_f32 v[54:55], v[54:55], v[80:81]
	v_pk_add_f32 v[52:53], v[52:53], v[86:87]
	v_pk_add_f32 v[54:55], v[54:55], v[84:85]
	v_pk_add_f32 v[52:53], v[52:53], v[90:91]
	v_pk_add_f32 v[54:55], v[54:55], v[88:89]
	v_pk_add_f32 v[52:53], v[52:53], v[94:95]
	v_pk_add_f32 v[54:55], v[54:55], v[92:93]
	v_pk_add_f32 v[52:53], v[52:53], v[98:99]
	v_pk_add_f32 v[54:55], v[54:55], v[96:97]
	v_pk_add_f32 v[52:53], v[52:53], v[102:103]
	v_pk_add_f32 v[54:55], v[54:55], v[100:101]
	v_pk_fma_f32 v[2:3], v[52:53], v[68:69], v[2:3]
	v_pk_fma_f32 v[0:1], v[54:55], v[66:67], v[0:1]
	global_store_dwordx4 v[44:45], v[0:3], off offset:-3072
	v_mul_f32_e32 v47, v3, v3
	v_mul_f32_e32 v46, v1, v1
	v_fmac_f32_e32 v46, v0, v0
	v_fmac_f32_e32 v47, v2, v2
	v_add_f32_e32 v46, v46, v47
	v_mov_b32_e32 v70, v46
	s_waitcnt vmcnt(2)
; __device__ __forceinline__ void phase_xs_ctx(Ctx& F, float* xctx, const float* part, const float* gate4, const float* g, const float* modl, float* ss1, bf16* XS) {
;     ...
;         for (int j = 0; j < 4; ++j) { const int c = 256 * j + 4 * lane; f32x4 a = {0.f, 0.f, 0.f, 0.f};
; #pragma unroll
;             for (int ks = 0; ks < KSPLIT; ++ks) a += *(const f32x4*)(part + ((size_t)ks * MC + r) * DM + c);
;             v[j] = *(const f32x4*)(xr + c) + *(const f32x4*)(gate4 + c) * a; *(f32x4*)(xr + c) = v[j];
;             ss += (v[j][0] * v[j][0] + v[j][1] * v[j][1]) + (v[j][2] * v[j][2] + v[j][3] * v[j][3]); }
;         ss = wave_sum(ss);
;         if (lane == 0) ss1[row] = ss;
	v_pk_add_f32 v[52:53], v[106:107], 0 op_sel_hi:[1,0]
	v_pk_add_f32 v[54:55], v[104:105], 0 op_sel_hi:[1,0]
	v_pk_add_f32 v[52:53], v[52:53], v[110:111]
	v_pk_add_f32 v[54:55], v[54:55], v[108:109]
	v_pk_add_f32 v[52:53], v[52:53], v[114:115]
	v_pk_add_f32 v[54:55], v[54:55], v[112:113]
	v_pk_add_f32 v[52:53], v[52:53], v[118:119]
	v_pk_add_f32 v[54:55], v[54:55], v[116:117]
	v_pk_add_f32 v[52:53], v[52:53], v[122:123]
	v_pk_add_f32 v[54:55], v[54:55], v[120:121]
	v_pk_add_f32 v[52:53], v[52:53], v[126:127]
	v_pk_add_f32 v[54:55], v[54:55], v[124:125]
	v_pk_add_f32 v[52:53], v[52:53], v[130:131]
	v_pk_add_f32 v[54:55], v[54:55], v[128:129]
	v_pk_add_f32 v[52:53], v[52:53], v[134:135]
	v_pk_add_f32 v[54:55], v[54:55], v[132:133]
	v_pk_fma_f32 v[6:7], v[52:53], v[202:203], v[6:7]
	v_pk_fma_f32 v[4:5], v[54:55], v[200:201], v[4:5]
	global_store_dwordx4 v[44:45], v[4:7], off offset:-2048
	v_mul_f32_e32 v47, v7, v7
	v_mul_f32_e32 v46, v5, v5
	v_fmac_f32_e32 v46, v4, v4
	v_fmac_f32_e32 v47, v6, v6
	v_add_f32_e32 v46, v46, v47
	v_add_f32_e32 v70, v70, v46
	s_waitcnt vmcnt(1)
	v_pk_add_f32 v[52:53], v[138:139], 0 op_sel_hi:[1,0]
	v_pk_add_f32 v[54:55], v[136:137], 0 op_sel_hi:[1,0]
	v_pk_add_f32 v[52:53], v[52:53], v[142:143]
	v_pk_add_f32 v[54:55], v[54:55], v[140:141]
	v_pk_add_f32 v[52:53], v[52:53], v[146:147]
	v_pk_add_f32 v[54:55], v[54:55], v[144:145]
	v_pk_add_f32 v[52:53], v[52:53], v[150:151]
	v_pk_add_f32 v[54:55], v[54:55], v[148:149]
	v_pk_add_f32 v[52:53], v[52:53], v[154:155]
	v_pk_add_f32 v[54:55], v[54:55], v[152:153]
	v_pk_add_f32 v[52:53], v[52:53], v[158:159]
	v_pk_add_f32 v[54:55], v[54:55], v[156:157]
	v_pk_add_f32 v[52:53], v[52:53], v[162:163]
	v_pk_add_f32 v[54:55], v[54:55], v[160:161]
	v_pk_add_f32 v[52:53], v[52:53], v[166:167]
	v_pk_add_f32 v[54:55], v[54:55], v[164:165]
	v_pk_fma_f32 v[10:11], v[52:53], v[64:65], v[10:11]
	v_pk_fma_f32 v[8:9], v[54:55], v[62:63], v[8:9]
	global_store_dwordx4 v[44:45], v[8:11], off offset:-1024
	v_mul_f32_e32 v47, v11, v11
	v_mul_f32_e32 v46, v9, v9
	v_fmac_f32_e32 v46, v8, v8
	v_fmac_f32_e32 v47, v10, v10
	v_add_f32_e32 v46, v46, v47
	v_add_f32_e32 v70, v70, v46
	s_waitcnt vmcnt(0)
	v_pk_add_f32 v[52:53], v[170:171], 0 op_sel_hi:[1,0]
	v_pk_add_f32 v[54:55], v[168:169], 0 op_sel_hi:[1,0]
	v_pk_add_f32 v[52:53], v[52:53], v[174:175]
	v_pk_add_f32 v[54:55], v[54:55], v[172:173]
	v_pk_add_f32 v[52:53], v[52:53], v[178:179]
	v_pk_add_f32 v[54:55], v[54:55], v[176:177]
	v_pk_add_f32 v[52:53], v[52:53], v[182:183]
	v_pk_add_f32 v[54:55], v[54:55], v[180:181]
	v_pk_add_f32 v[52:53], v[52:53], v[186:187]
	v_pk_add_f32 v[54:55], v[54:55], v[184:185]
	v_pk_add_f32 v[52:53], v[52:53], v[190:191]
	v_pk_add_f32 v[54:55], v[54:55], v[188:189]
	v_pk_add_f32 v[52:53], v[52:53], v[194:195]
	v_pk_add_f32 v[54:55], v[54:55], v[192:193]
	v_pk_add_f32 v[52:53], v[52:53], v[198:199]
	v_pk_add_f32 v[54:55], v[54:55], v[196:197]
	v_pk_fma_f32 v[14:15], v[52:53], v[50:51], v[14:15]
	v_pk_fma_f32 v[12:13], v[54:55], v[48:49], v[12:13]
	global_store_dwordx4 v[44:45], v[12:15], off
	v_mul_f32_e32 v47, v15, v15
	v_mul_f32_e32 v46, v13, v13
	v_fmac_f32_e32 v46, v12, v12
	v_fmac_f32_e32 v47, v14, v14
	v_add_f32_e32 v46, v46, v47
	v_add_f32_e32 v44, v70, v46
	ds_bpermute_b32 v45, v56, v44
	s_waitcnt lgkmcnt(0)
	v_add_f32_e32 v44, v44, v45
	ds_bpermute_b32 v45, v57, v44
	s_waitcnt lgkmcnt(0)
	v_add_f32_e32 v44, v44, v45
	ds_bpermute_b32 v45, v58, v44
	s_waitcnt lgkmcnt(0)
	v_add_f32_e32 v44, v44, v45
	ds_bpermute_b32 v45, v59, v44
	s_waitcnt lgkmcnt(0)
	v_add_f32_e32 v44, v44, v45
	ds_bpermute_b32 v45, v60, v44
	s_waitcnt lgkmcnt(0)
	v_add_f32_e32 v44, v44, v45
	ds_bpermute_b32 v45, v61, v44
	s_and_saveexec_b64 s[10:11], s[4:5]
	s_cbranch_execz .LBB0_24
	s_lshl_b64 s[16:17], s[8:9], 2
	s_add_u32 s16, s13, s16
	s_addc_u32 s17, s14, s17
	s_waitcnt lgkmcnt(0)
	v_add_f32_e32 v44, v44, v45
	global_store_dword v205, v44, s[16:17]
	s_branch .LBB0_24
